# baseline (speedup 1.0000x reference)
.Lkv_k_body_ctx:
	v_lshlrev_b32_e32 v132, s84, v130
	v_lshl_add_u32 v132, v131, 1, v132
	s_lshl_b32 s58, 16, s84
	s_mul_i32 s59, s58, 5
	v_cvt_pk_bf16_f32 v134, v126, v127
	v_cvt_pk_bf16_f32 v135, v128, v129
	global_store_dwordx2 v132, v[134:135], s[6:7] offset:0
	v_cvt_pk_bf16_f32 v136, v122, v123
	v_cvt_pk_bf16_f32 v137, v124, v125
	global_store_dwordx2 v132, v[136:137], s[6:7] offset:32
	v_cvt_pk_bf16_f32 v138, v94, v95
	v_cvt_pk_bf16_f32 v139, v96, v97
	global_store_dwordx2 v132, v[138:139], s[6:7] offset:256
	v_cvt_pk_bf16_f32 v140, v90, v91
	v_cvt_pk_bf16_f32 v141, v92, v93
	global_store_dwordx2 v132, v[140:141], s[6:7] offset:288
	s_add_u32 s6, s6, s58
	s_addc_u32 s7, s7, 0
	v_cvt_pk_bf16_f32 v142, v118, v119
	v_cvt_pk_bf16_f32 v143, v120, v121
	global_store_dwordx2 v132, v[142:143], s[6:7] offset:0
	v_cvt_pk_bf16_f32 v144, v114, v115
	v_cvt_pk_bf16_f32 v145, v116, v117
	global_store_dwordx2 v132, v[144:145], s[6:7] offset:32
	v_cvt_pk_bf16_f32 v146, v86, v87
	v_cvt_pk_bf16_f32 v147, v88, v89
	global_store_dwordx2 v132, v[146:147], s[6:7] offset:256
	v_cvt_pk_bf16_f32 v148, v82, v83
	v_cvt_pk_bf16_f32 v149, v84, v85
	global_store_dwordx2 v132, v[148:149], s[6:7] offset:288
	s_add_u32 s6, s6, s58
	s_addc_u32 s7, s7, 0
	v_cvt_pk_bf16_f32 v150, v110, v111
	v_cvt_pk_bf16_f32 v151, v112, v113
	global_store_dwordx2 v132, v[150:151], s[6:7] offset:0
	v_cvt_pk_bf16_f32 v152, v106, v107
	v_cvt_pk_bf16_f32 v153, v108, v109
	global_store_dwordx2 v132, v[152:153], s[6:7] offset:32
	v_cvt_pk_bf16_f32 v154, v78, v79
	v_cvt_pk_bf16_f32 v155, v80, v81
	global_store_dwordx2 v132, v[154:155], s[6:7] offset:256
	v_cvt_pk_bf16_f32 v156, v74, v75
	v_cvt_pk_bf16_f32 v157, v76, v77
	global_store_dwordx2 v132, v[156:157], s[6:7] offset:288
	s_add_u32 s6, s6, s58
	s_addc_u32 s7, s7, 0
	v_cvt_pk_bf16_f32 v158, v102, v103
	v_cvt_pk_bf16_f32 v159, v104, v105
	global_store_dwordx2 v132, v[158:159], s[6:7] offset:0
	v_cvt_pk_bf16_f32 v160, v98, v99
	v_cvt_pk_bf16_f32 v161, v100, v101
	global_store_dwordx2 v132, v[160:161], s[6:7] offset:32
	v_cvt_pk_bf16_f32 v162, v70, v71
	v_cvt_pk_bf16_f32 v163, v72, v73
	global_store_dwordx2 v132, v[162:163], s[6:7] offset:256
	v_cvt_pk_bf16_f32 v164, v66, v67
	v_cvt_pk_bf16_f32 v165, v68, v69
	global_store_dwordx2 v132, v[164:165], s[6:7] offset:288
	s_add_u32 s6, s6, s59
	s_addc_u32 s7, s7, 0
	v_cvt_pk_bf16_f32 v134, v62, v63
	v_cvt_pk_bf16_f32 v135, v64, v65
	global_store_dwordx2 v132, v[134:135], s[6:7] offset:0
	v_cvt_pk_bf16_f32 v136, v58, v59
	v_cvt_pk_bf16_f32 v137, v60, v61
	global_store_dwordx2 v132, v[136:137], s[6:7] offset:32
	v_cvt_pk_bf16_f32 v138, v30, v31
	v_cvt_pk_bf16_f32 v139, v32, v33
	global_store_dwordx2 v132, v[138:139], s[6:7] offset:256
	v_cvt_pk_bf16_f32 v140, v26, v27
	v_cvt_pk_bf16_f32 v141, v28, v29
	global_store_dwordx2 v132, v[140:141], s[6:7] offset:288
	s_add_u32 s6, s6, s58
	s_addc_u32 s7, s7, 0
	v_cvt_pk_bf16_f32 v142, v54, v55
	v_cvt_pk_bf16_f32 v143, v56, v57
	global_store_dwordx2 v132, v[142:143], s[6:7] offset:0
	v_cvt_pk_bf16_f32 v144, v50, v51
	v_cvt_pk_bf16_f32 v145, v52, v53
	global_store_dwordx2 v132, v[144:145], s[6:7] offset:32
	v_cvt_pk_bf16_f32 v146, v22, v23
	v_cvt_pk_bf16_f32 v147, v24, v25
	global_store_dwordx2 v132, v[146:147], s[6:7] offset:256
	v_cvt_pk_bf16_f32 v148, v18, v19
	v_cvt_pk_bf16_f32 v149, v20, v21
	global_store_dwordx2 v132, v[148:149], s[6:7] offset:288
	s_add_u32 s6, s6, s58
	s_addc_u32 s7, s7, 0
	v_cvt_pk_bf16_f32 v150, v46, v47
	v_cvt_pk_bf16_f32 v151, v48, v49
	global_store_dwordx2 v132, v[150:151], s[6:7] offset:0
	v_cvt_pk_bf16_f32 v152, v42, v43
	v_cvt_pk_bf16_f32 v153, v44, v45
	global_store_dwordx2 v132, v[152:153], s[6:7] offset:32
	v_cvt_pk_bf16_f32 v154, v14, v15
	v_cvt_pk_bf16_f32 v155, v16, v17
	global_store_dwordx2 v132, v[154:155], s[6:7] offset:256
	v_cvt_pk_bf16_f32 v156, v10, v11
	v_cvt_pk_bf16_f32 v157, v12, v13
	global_store_dwordx2 v132, v[156:157], s[6:7] offset:288
	s_add_u32 s6, s6, s58
	s_addc_u32 s7, s7, 0
	v_cvt_pk_bf16_f32 v158, v38, v39
	v_cvt_pk_bf16_f32 v159, v40, v41
	global_store_dwordx2 v132, v[158:159], s[6:7] offset:0
	v_cvt_pk_bf16_f32 v160, v34, v35
	v_cvt_pk_bf16_f32 v161, v36, v37
	global_store_dwordx2 v132, v[160:161], s[6:7] offset:32
	v_cvt_pk_bf16_f32 v162, v6, v7
	v_cvt_pk_bf16_f32 v163, v8, v9
	global_store_dwordx2 v132, v[162:163], s[6:7] offset:256
	v_cvt_pk_bf16_f32 v164, v2, v3
	v_cvt_pk_bf16_f32 v165, v4, v5
	global_store_dwordx2 v132, v[164:165], s[6:7] offset:288
	v_readfirstlane_b32 s28, v190
	s_nop 3
	s_lshr_b32 s28, s28, 6
	s_lshr_b32 s29, s28, 2
	s_and_b32 s30, s28, 3
	v_and_b32_e32 v172, 15, v190
	v_bfe_u32 v173, v190, 4, 2
	v_and_b32_e32 v174, 7, v172
	v_xor_b32_e32 v175, v173, v174
	v_add_u32_e32 v176, 4, v173
	v_xor_b32_e32 v176, v176, v174
	v_lshlrev_b32_e32 v177, 10, v172
	s_lshl_b32 s31, s30, 7
	v_add_u32_e32 v177, s31, v177
	v_lshl_add_u32 v178, v175, 4, v177
	v_lshl_add_u32 v179, v176, 4, v177
	v_add_u32_e32 v180, 0x10000, v178
	v_add_u32_e32 v181, 0x10000, v179
	v_and_b32_e32 v182, 63, v190
	v_lshlrev_b32_e32 v182, 4, v182
	s_lshl_b32 s44, s30, 13
	s_lshl_b32 s45, s29, 16
	s_add_i32 s44, s44, s45
	s_add_i32 s44, s44, 0x8000
	v_mov_b32_e32 v183, s44
	s_lshl_b32 s45, s28, 3
	s_lshl_b32 s45, s45, s85
	v_add_u32_e32 v184, s45, v182
	s_lshl_b32 s46, 64, s85
	s_lshl_b32 s47, 1, s85
	s_cmp_eq_u32 s29, 0
	s_cbranch_scc0 .Lkvst_k_0
	ds_write_b128 v178, v[126:129] offset:32768
	ds_write_b128 v179, v[122:125] offset:32768
	ds_write_b128 v178, v[94:97] offset:33280
	ds_write_b128 v179, v[90:93] offset:33280
	ds_write_b128 v178, v[118:121] offset:49152
	ds_write_b128 v179, v[114:117] offset:49152
	ds_write_b128 v178, v[86:89] offset:49664
	ds_write_b128 v179, v[82:85] offset:49664
	ds_write_b128 v180, v[110:113] offset:32768
	ds_write_b128 v181, v[106:109] offset:32768
	ds_write_b128 v180, v[78:81] offset:33280
	ds_write_b128 v181, v[74:77] offset:33280
	ds_write_b128 v180, v[102:105] offset:49152
	ds_write_b128 v181, v[98:101] offset:49152
	ds_write_b128 v180, v[70:73] offset:49664
	ds_write_b128 v181, v[66:69] offset:49664
.Lkvst_k_0:
	s_waitcnt lgkmcnt(0)
	s_barrier
	v_xor_b32_e32 v132, 0, v182
	v_add_u32_e32 v132, v183, v132
	ds_read_b128 v[140:143], v132 offset:0
	v_xor_b32_e32 v133, 16, v182
	v_add_u32_e32 v133, v183, v133
	ds_read_b128 v[144:147], v133 offset:1024
	v_xor_b32_e32 v134, 32, v182
	v_add_u32_e32 v134, v183, v134
	ds_read_b128 v[148:151], v134 offset:2048
	v_xor_b32_e32 v135, 48, v182
	v_add_u32_e32 v135, v183, v135
	ds_read_b128 v[152:155], v135 offset:3072
	v_xor_b32_e32 v136, 64, v182
	v_add_u32_e32 v136, v183, v136
	ds_read_b128 v[156:159], v136 offset:4096
	v_xor_b32_e32 v137, 80, v182
	v_add_u32_e32 v137, v183, v137
	ds_read_b128 v[160:163], v137 offset:5120
	v_xor_b32_e32 v138, 96, v182
	v_add_u32_e32 v138, v183, v138
	ds_read_b128 v[164:167], v138 offset:6144
	v_xor_b32_e32 v139, 112, v182
	v_add_u32_e32 v139, v183, v139
	ds_read_b128 v[168:171], v139 offset:7168
	s_mov_b32 s24, s8
	s_mov_b32 s25, s9
	s_waitcnt lgkmcnt(7)
	global_store_dwordx4 v184, v[140:143], s[24:25]
	s_add_u32 s24, s24, s47
	s_addc_u32 s25, s25, 0
	s_waitcnt lgkmcnt(6)
	global_store_dwordx4 v184, v[144:147], s[24:25]
	s_add_u32 s24, s24, s47
	s_addc_u32 s25, s25, 0
	s_waitcnt lgkmcnt(5)
	global_store_dwordx4 v184, v[148:151], s[24:25]
	s_add_u32 s24, s24, s47
	s_addc_u32 s25, s25, 0
	s_waitcnt lgkmcnt(4)
	global_store_dwordx4 v184, v[152:155], s[24:25]
	s_add_u32 s24, s24, s47
	s_addc_u32 s25, s25, 0
	s_waitcnt lgkmcnt(3)
	global_store_dwordx4 v184, v[156:159], s[24:25]
	s_add_u32 s24, s24, s47
	s_addc_u32 s25, s25, 0
	s_waitcnt lgkmcnt(2)
	global_store_dwordx4 v184, v[160:163], s[24:25]
	s_add_u32 s24, s24, s47
	s_addc_u32 s25, s25, 0
	s_waitcnt lgkmcnt(1)
	global_store_dwordx4 v184, v[164:167], s[24:25]
	s_add_u32 s24, s24, s47
	s_addc_u32 s25, s25, 0
	s_waitcnt lgkmcnt(0)
	global_store_dwordx4 v184, v[168:171], s[24:25]
	s_barrier
	s_add_u32 s8, s8, s46
	s_addc_u32 s9, s9, 0
	s_cmp_eq_u32 s29, 1
	s_cbranch_scc0 .Lkvst_k_1
	ds_write_b128 v178, v[126:129] offset:32768
	ds_write_b128 v179, v[122:125] offset:32768
	ds_write_b128 v178, v[94:97] offset:33280
	ds_write_b128 v179, v[90:93] offset:33280
	ds_write_b128 v178, v[118:121] offset:49152
	ds_write_b128 v179, v[114:117] offset:49152
	ds_write_b128 v178, v[86:89] offset:49664
	ds_write_b128 v179, v[82:85] offset:49664
	ds_write_b128 v180, v[110:113] offset:32768
	ds_write_b128 v181, v[106:109] offset:32768
	ds_write_b128 v180, v[78:81] offset:33280
	ds_write_b128 v181, v[74:77] offset:33280
	ds_write_b128 v180, v[102:105] offset:49152
	ds_write_b128 v181, v[98:101] offset:49152
	ds_write_b128 v180, v[70:73] offset:49664
	ds_write_b128 v181, v[66:69] offset:49664
.Lkvst_k_1:
	s_waitcnt lgkmcnt(0)
	s_barrier
	v_xor_b32_e32 v132, 0, v182
	v_add_u32_e32 v132, v183, v132
	ds_read_b128 v[140:143], v132 offset:0
	v_xor_b32_e32 v133, 16, v182
	v_add_u32_e32 v133, v183, v133
	ds_read_b128 v[144:147], v133 offset:1024
	v_xor_b32_e32 v134, 32, v182
	v_add_u32_e32 v134, v183, v134
	ds_read_b128 v[148:151], v134 offset:2048
	v_xor_b32_e32 v135, 48, v182
	v_add_u32_e32 v135, v183, v135
	ds_read_b128 v[152:155], v135 offset:3072
	v_xor_b32_e32 v136, 64, v182
	v_add_u32_e32 v136, v183, v136
	ds_read_b128 v[156:159], v136 offset:4096
	v_xor_b32_e32 v137, 80, v182
	v_add_u32_e32 v137, v183, v137
	ds_read_b128 v[160:163], v137 offset:5120
	v_xor_b32_e32 v138, 96, v182
	v_add_u32_e32 v138, v183, v138
	ds_read_b128 v[164:167], v138 offset:6144
	v_xor_b32_e32 v139, 112, v182
	v_add_u32_e32 v139, v183, v139
	ds_read_b128 v[168:171], v139 offset:7168
	s_mov_b32 s24, s8
	s_mov_b32 s25, s9
	s_waitcnt lgkmcnt(7)
	global_store_dwordx4 v184, v[140:143], s[24:25]
	s_add_u32 s24, s24, s47
	s_addc_u32 s25, s25, 0
	s_waitcnt lgkmcnt(6)
	global_store_dwordx4 v184, v[144:147], s[24:25]
	s_add_u32 s24, s24, s47
	s_addc_u32 s25, s25, 0
	s_waitcnt lgkmcnt(5)
	global_store_dwordx4 v184, v[148:151], s[24:25]
	s_add_u32 s24, s24, s47
	s_addc_u32 s25, s25, 0
	s_waitcnt lgkmcnt(4)
	global_store_dwordx4 v184, v[152:155], s[24:25]
	s_add_u32 s24, s24, s47
	s_addc_u32 s25, s25, 0
	s_waitcnt lgkmcnt(3)
	global_store_dwordx4 v184, v[156:159], s[24:25]
	s_add_u32 s24, s24, s47
	s_addc_u32 s25, s25, 0
	s_waitcnt lgkmcnt(2)
	global_store_dwordx4 v184, v[160:163], s[24:25]
	s_add_u32 s24, s24, s47
	s_addc_u32 s25, s25, 0
	s_waitcnt lgkmcnt(1)
	global_store_dwordx4 v184, v[164:167], s[24:25]
	s_add_u32 s24, s24, s47
	s_addc_u32 s25, s25, 0
	s_waitcnt lgkmcnt(0)
	global_store_dwordx4 v184, v[168:171], s[24:25]
	s_barrier
	s_add_u32 s8, s8, s46
	s_addc_u32 s9, s9, 0
	s_cmp_eq_u32 s29, 0
	s_cbranch_scc0 .Lkvst_k_2
	ds_write_b128 v178, v[62:65] offset:32768
	ds_write_b128 v179, v[58:61] offset:32768
	ds_write_b128 v178, v[30:33] offset:33280
	ds_write_b128 v179, v[26:29] offset:33280
	ds_write_b128 v178, v[54:57] offset:49152
	ds_write_b128 v179, v[50:53] offset:49152
	ds_write_b128 v178, v[22:25] offset:49664
	ds_write_b128 v179, v[18:21] offset:49664
	ds_write_b128 v180, v[46:49] offset:32768
	ds_write_b128 v181, v[42:45] offset:32768
	ds_write_b128 v180, v[14:17] offset:33280
	ds_write_b128 v181, v[10:13] offset:33280
	ds_write_b128 v180, v[38:41] offset:49152
	ds_write_b128 v181, v[34:37] offset:49152
	ds_write_b128 v180, v[6:9] offset:49664
	ds_write_b128 v181, v[2:5] offset:49664
.Lkvst_k_2:
	s_waitcnt lgkmcnt(0)
	s_barrier
	v_xor_b32_e32 v132, 0, v182
	v_add_u32_e32 v132, v183, v132
	ds_read_b128 v[140:143], v132 offset:0
	v_xor_b32_e32 v133, 16, v182
	v_add_u32_e32 v133, v183, v133
	ds_read_b128 v[144:147], v133 offset:1024
	v_xor_b32_e32 v134, 32, v182
	v_add_u32_e32 v134, v183, v134
	ds_read_b128 v[148:151], v134 offset:2048
	v_xor_b32_e32 v135, 48, v182
	v_add_u32_e32 v135, v183, v135
	ds_read_b128 v[152:155], v135 offset:3072
	v_xor_b32_e32 v136, 64, v182
	v_add_u32_e32 v136, v183, v136
	ds_read_b128 v[156:159], v136 offset:4096
	v_xor_b32_e32 v137, 80, v182
	v_add_u32_e32 v137, v183, v137
	ds_read_b128 v[160:163], v137 offset:5120
	v_xor_b32_e32 v138, 96, v182
	v_add_u32_e32 v138, v183, v138
	ds_read_b128 v[164:167], v138 offset:6144
	v_xor_b32_e32 v139, 112, v182
	v_add_u32_e32 v139, v183, v139
	ds_read_b128 v[168:171], v139 offset:7168
	s_mov_b32 s24, s8
	s_mov_b32 s25, s9
	s_waitcnt lgkmcnt(7)
	global_store_dwordx4 v184, v[140:143], s[24:25]
	s_add_u32 s24, s24, s47
	s_addc_u32 s25, s25, 0
	s_waitcnt lgkmcnt(6)
	global_store_dwordx4 v184, v[144:147], s[24:25]
	s_add_u32 s24, s24, s47
	s_addc_u32 s25, s25, 0
	s_waitcnt lgkmcnt(5)
	global_store_dwordx4 v184, v[148:151], s[24:25]
	s_add_u32 s24, s24, s47
	s_addc_u32 s25, s25, 0
	s_waitcnt lgkmcnt(4)
	global_store_dwordx4 v184, v[152:155], s[24:25]
	s_add_u32 s24, s24, s47
	s_addc_u32 s25, s25, 0
	s_waitcnt lgkmcnt(3)
	global_store_dwordx4 v184, v[156:159], s[24:25]
	s_add_u32 s24, s24, s47
	s_addc_u32 s25, s25, 0
	s_waitcnt lgkmcnt(2)
	global_store_dwordx4 v184, v[160:163], s[24:25]
	s_add_u32 s24, s24, s47
	s_addc_u32 s25, s25, 0
	s_waitcnt lgkmcnt(1)
	global_store_dwordx4 v184, v[164:167], s[24:25]
	s_add_u32 s24, s24, s47
	s_addc_u32 s25, s25, 0
	s_waitcnt lgkmcnt(0)
	global_store_dwordx4 v184, v[168:171], s[24:25]
	s_barrier
	s_add_u32 s8, s8, s46
	s_addc_u32 s9, s9, 0
	s_cmp_eq_u32 s29, 1
	s_cbranch_scc0 .Lkvst_k_3
	ds_write_b128 v178, v[62:65] offset:32768
	ds_write_b128 v179, v[58:61] offset:32768
	ds_write_b128 v178, v[30:33] offset:33280
	ds_write_b128 v179, v[26:29] offset:33280
	ds_write_b128 v178, v[54:57] offset:49152
	ds_write_b128 v179, v[50:53] offset:49152
	ds_write_b128 v178, v[22:25] offset:49664
	ds_write_b128 v179, v[18:21] offset:49664
	ds_write_b128 v180, v[46:49] offset:32768
	ds_write_b128 v181, v[42:45] offset:32768
	ds_write_b128 v180, v[14:17] offset:33280
	ds_write_b128 v181, v[10:13] offset:33280
	ds_write_b128 v180, v[38:41] offset:49152
	ds_write_b128 v181, v[34:37] offset:49152
	ds_write_b128 v180, v[6:9] offset:49664
	ds_write_b128 v181, v[2:5] offset:49664
.Lkvst_k_3:
	s_waitcnt lgkmcnt(0)
	s_barrier
	v_xor_b32_e32 v132, 0, v182
	v_add_u32_e32 v132, v183, v132
	ds_read_b128 v[140:143], v132 offset:0
	v_xor_b32_e32 v133, 16, v182
	v_add_u32_e32 v133, v183, v133
	ds_read_b128 v[144:147], v133 offset:1024
	v_xor_b32_e32 v134, 32, v182
	v_add_u32_e32 v134, v183, v134
	ds_read_b128 v[148:151], v134 offset:2048
	v_xor_b32_e32 v135, 48, v182
	v_add_u32_e32 v135, v183, v135
	ds_read_b128 v[152:155], v135 offset:3072
	v_xor_b32_e32 v136, 64, v182
	v_add_u32_e32 v136, v183, v136
	ds_read_b128 v[156:159], v136 offset:4096
	v_xor_b32_e32 v137, 80, v182
	v_add_u32_e32 v137, v183, v137
	ds_read_b128 v[160:163], v137 offset:5120
	v_xor_b32_e32 v138, 96, v182
	v_add_u32_e32 v138, v183, v138
	ds_read_b128 v[164:167], v138 offset:6144
	v_xor_b32_e32 v139, 112, v182
	v_add_u32_e32 v139, v183, v139
	ds_read_b128 v[168:171], v139 offset:7168
	s_mov_b32 s24, s8
	s_mov_b32 s25, s9
	s_waitcnt lgkmcnt(7)
	global_store_dwordx4 v184, v[140:143], s[24:25]
	s_add_u32 s24, s24, s47
	s_addc_u32 s25, s25, 0
	s_waitcnt lgkmcnt(6)
	global_store_dwordx4 v184, v[144:147], s[24:25]
	s_add_u32 s24, s24, s47
	s_addc_u32 s25, s25, 0
	s_waitcnt lgkmcnt(5)
	global_store_dwordx4 v184, v[148:151], s[24:25]
	s_add_u32 s24, s24, s47
	s_addc_u32 s25, s25, 0
	s_waitcnt lgkmcnt(4)
	global_store_dwordx4 v184, v[152:155], s[24:25]
	s_add_u32 s24, s24, s47
	s_addc_u32 s25, s25, 0
	s_waitcnt lgkmcnt(3)
	global_store_dwordx4 v184, v[156:159], s[24:25]
	s_add_u32 s24, s24, s47
	s_addc_u32 s25, s25, 0
	s_waitcnt lgkmcnt(2)
	global_store_dwordx4 v184, v[160:163], s[24:25]
	s_add_u32 s24, s24, s47
	s_addc_u32 s25, s25, 0
	s_waitcnt lgkmcnt(1)
	global_store_dwordx4 v184, v[164:167], s[24:25]
	s_add_u32 s24, s24, s47
	s_addc_u32 s25, s25, 0
	s_waitcnt lgkmcnt(0)
	global_store_dwordx4 v184, v[168:171], s[24:25]
	s_barrier
	s_branch .LBB0_247

.Lkv_v_body_ctx:
	v_mul_u32_u24_e32 v132, s76, v131
	v_lshl_add_u32 v132, v130, 1, v132
	s_mul_i32 s77, s76, 13
	s_mul_i32 s60, s76, 109
	v_cvt_pk_bf16_f32 v134, v126, v127
	v_cvt_pk_bf16_f32 v135, v128, v129
	v_cvt_pk_bf16_f32 v136, v118, v119
	v_cvt_pk_bf16_f32 v137, v120, v121
	v_cvt_pk_bf16_f32 v138, v110, v111
	v_cvt_pk_bf16_f32 v139, v112, v113
	v_cvt_pk_bf16_f32 v140, v102, v103
	v_cvt_pk_bf16_f32 v141, v104, v105
	v_cvt_pk_bf16_f32 v142, v62, v63
	v_cvt_pk_bf16_f32 v143, v64, v65
	v_cvt_pk_bf16_f32 v144, v54, v55
	v_cvt_pk_bf16_f32 v145, v56, v57
	v_cvt_pk_bf16_f32 v146, v46, v47
	v_cvt_pk_bf16_f32 v147, v48, v49
	v_cvt_pk_bf16_f32 v148, v38, v39
	v_cvt_pk_bf16_f32 v149, v40, v41
	global_store_short v132, v134, s[6:7] offset:0
	global_store_short v132, v136, s[6:7] offset:32
	global_store_short v132, v138, s[6:7] offset:64
	global_store_short v132, v140, s[6:7] offset:96
	global_store_short v132, v142, s[6:7] offset:256
	global_store_short v132, v144, s[6:7] offset:288
	global_store_short v132, v146, s[6:7] offset:320
	global_store_short v132, v148, s[6:7] offset:352
	s_add_u32 s6, s6, s76
	s_addc_u32 s7, s7, 0
	global_store_short_d16_hi v132, v134, s[6:7] offset:0
	global_store_short_d16_hi v132, v136, s[6:7] offset:32
	global_store_short_d16_hi v132, v138, s[6:7] offset:64
	global_store_short_d16_hi v132, v140, s[6:7] offset:96
	global_store_short_d16_hi v132, v142, s[6:7] offset:256
	global_store_short_d16_hi v132, v144, s[6:7] offset:288
	global_store_short_d16_hi v132, v146, s[6:7] offset:320
	global_store_short_d16_hi v132, v148, s[6:7] offset:352
	s_add_u32 s6, s6, s76
	s_addc_u32 s7, s7, 0
	global_store_short v132, v135, s[6:7] offset:0
	global_store_short v132, v137, s[6:7] offset:32
	global_store_short v132, v139, s[6:7] offset:64
	global_store_short v132, v141, s[6:7] offset:96
	global_store_short v132, v143, s[6:7] offset:256
	global_store_short v132, v145, s[6:7] offset:288
	global_store_short v132, v147, s[6:7] offset:320
	global_store_short v132, v149, s[6:7] offset:352
	s_add_u32 s6, s6, s76
	s_addc_u32 s7, s7, 0
	global_store_short_d16_hi v132, v135, s[6:7] offset:0
	global_store_short_d16_hi v132, v137, s[6:7] offset:32
	global_store_short_d16_hi v132, v139, s[6:7] offset:64
	global_store_short_d16_hi v132, v141, s[6:7] offset:96
	global_store_short_d16_hi v132, v143, s[6:7] offset:256
	global_store_short_d16_hi v132, v145, s[6:7] offset:288
	global_store_short_d16_hi v132, v147, s[6:7] offset:320
	global_store_short_d16_hi v132, v149, s[6:7] offset:352
	s_add_u32 s6, s6, s77
	s_addc_u32 s7, s7, 0
	v_cvt_pk_bf16_f32 v150, v122, v123
	v_cvt_pk_bf16_f32 v151, v124, v125
	v_cvt_pk_bf16_f32 v152, v114, v115
	v_cvt_pk_bf16_f32 v153, v116, v117
	v_cvt_pk_bf16_f32 v154, v106, v107
	v_cvt_pk_bf16_f32 v155, v108, v109
	v_cvt_pk_bf16_f32 v156, v98, v99
	v_cvt_pk_bf16_f32 v157, v100, v101
	v_cvt_pk_bf16_f32 v158, v58, v59
	v_cvt_pk_bf16_f32 v159, v60, v61
	v_cvt_pk_bf16_f32 v160, v50, v51
	v_cvt_pk_bf16_f32 v161, v52, v53
	v_cvt_pk_bf16_f32 v162, v42, v43
	v_cvt_pk_bf16_f32 v163, v44, v45
	v_cvt_pk_bf16_f32 v164, v34, v35
	v_cvt_pk_bf16_f32 v165, v36, v37
	global_store_short v132, v150, s[6:7] offset:0
	global_store_short v132, v152, s[6:7] offset:32
	global_store_short v132, v154, s[6:7] offset:64
	global_store_short v132, v156, s[6:7] offset:96
	global_store_short v132, v158, s[6:7] offset:256
	global_store_short v132, v160, s[6:7] offset:288
	global_store_short v132, v162, s[6:7] offset:320
	global_store_short v132, v164, s[6:7] offset:352
	s_add_u32 s6, s6, s76
	s_addc_u32 s7, s7, 0
	global_store_short_d16_hi v132, v150, s[6:7] offset:0
	global_store_short_d16_hi v132, v152, s[6:7] offset:32
	global_store_short_d16_hi v132, v154, s[6:7] offset:64
	global_store_short_d16_hi v132, v156, s[6:7] offset:96
	global_store_short_d16_hi v132, v158, s[6:7] offset:256
	global_store_short_d16_hi v132, v160, s[6:7] offset:288
	global_store_short_d16_hi v132, v162, s[6:7] offset:320
	global_store_short_d16_hi v132, v164, s[6:7] offset:352
	s_add_u32 s6, s6, s76
	s_addc_u32 s7, s7, 0
	global_store_short v132, v151, s[6:7] offset:0
	global_store_short v132, v153, s[6:7] offset:32
	global_store_short v132, v155, s[6:7] offset:64
	global_store_short v132, v157, s[6:7] offset:96
	global_store_short v132, v159, s[6:7] offset:256
	global_store_short v132, v161, s[6:7] offset:288
	global_store_short v132, v163, s[6:7] offset:320
	global_store_short v132, v165, s[6:7] offset:352
	s_add_u32 s6, s6, s76
	s_addc_u32 s7, s7, 0
	global_store_short_d16_hi v132, v151, s[6:7] offset:0
	global_store_short_d16_hi v132, v153, s[6:7] offset:32
	global_store_short_d16_hi v132, v155, s[6:7] offset:64
	global_store_short_d16_hi v132, v157, s[6:7] offset:96
	global_store_short_d16_hi v132, v159, s[6:7] offset:256
	global_store_short_d16_hi v132, v161, s[6:7] offset:288
	global_store_short_d16_hi v132, v163, s[6:7] offset:320
	global_store_short_d16_hi v132, v165, s[6:7] offset:352
	s_add_u32 s6, s6, s60
	s_addc_u32 s7, s7, 0
	v_cvt_pk_bf16_f32 v134, v94, v95
	v_cvt_pk_bf16_f32 v135, v96, v97
	v_cvt_pk_bf16_f32 v136, v86, v87
	v_cvt_pk_bf16_f32 v137, v88, v89
	v_cvt_pk_bf16_f32 v138, v78, v79
	v_cvt_pk_bf16_f32 v139, v80, v81
	v_cvt_pk_bf16_f32 v140, v70, v71
	v_cvt_pk_bf16_f32 v141, v72, v73
	v_cvt_pk_bf16_f32 v142, v30, v31
	v_cvt_pk_bf16_f32 v143, v32, v33
	v_cvt_pk_bf16_f32 v144, v22, v23
	v_cvt_pk_bf16_f32 v145, v24, v25
	v_cvt_pk_bf16_f32 v146, v14, v15
	v_cvt_pk_bf16_f32 v147, v16, v17
	v_cvt_pk_bf16_f32 v148, v6, v7
	v_cvt_pk_bf16_f32 v149, v8, v9
	global_store_short v132, v134, s[6:7] offset:0
	global_store_short v132, v136, s[6:7] offset:32
	global_store_short v132, v138, s[6:7] offset:64
	global_store_short v132, v140, s[6:7] offset:96
	global_store_short v132, v142, s[6:7] offset:256
	global_store_short v132, v144, s[6:7] offset:288
	global_store_short v132, v146, s[6:7] offset:320
	global_store_short v132, v148, s[6:7] offset:352
	s_add_u32 s6, s6, s76
	s_addc_u32 s7, s7, 0
	global_store_short_d16_hi v132, v134, s[6:7] offset:0
	global_store_short_d16_hi v132, v136, s[6:7] offset:32
	global_store_short_d16_hi v132, v138, s[6:7] offset:64
	global_store_short_d16_hi v132, v140, s[6:7] offset:96
	global_store_short_d16_hi v132, v142, s[6:7] offset:256
	global_store_short_d16_hi v132, v144, s[6:7] offset:288
	global_store_short_d16_hi v132, v146, s[6:7] offset:320
	global_store_short_d16_hi v132, v148, s[6:7] offset:352
	s_add_u32 s6, s6, s76
	s_addc_u32 s7, s7, 0
	global_store_short v132, v135, s[6:7] offset:0
	global_store_short v132, v137, s[6:7] offset:32
	global_store_short v132, v139, s[6:7] offset:64
	global_store_short v132, v141, s[6:7] offset:96
	global_store_short v132, v143, s[6:7] offset:256
	global_store_short v132, v145, s[6:7] offset:288
	global_store_short v132, v147, s[6:7] offset:320
	global_store_short v132, v149, s[6:7] offset:352
	s_add_u32 s6, s6, s76
	s_addc_u32 s7, s7, 0
	global_store_short_d16_hi v132, v135, s[6:7] offset:0
	global_store_short_d16_hi v132, v137, s[6:7] offset:32
	global_store_short_d16_hi v132, v139, s[6:7] offset:64
	global_store_short_d16_hi v132, v141, s[6:7] offset:96
	global_store_short_d16_hi v132, v143, s[6:7] offset:256
	global_store_short_d16_hi v132, v145, s[6:7] offset:288
	global_store_short_d16_hi v132, v147, s[6:7] offset:320
	global_store_short_d16_hi v132, v149, s[6:7] offset:352
	s_add_u32 s6, s6, s77
	s_addc_u32 s7, s7, 0
	v_cvt_pk_bf16_f32 v150, v90, v91
	v_cvt_pk_bf16_f32 v151, v92, v93
	v_cvt_pk_bf16_f32 v152, v82, v83
	v_cvt_pk_bf16_f32 v153, v84, v85
	v_cvt_pk_bf16_f32 v154, v74, v75
	v_cvt_pk_bf16_f32 v155, v76, v77
	v_cvt_pk_bf16_f32 v156, v66, v67
	v_cvt_pk_bf16_f32 v157, v68, v69
	v_cvt_pk_bf16_f32 v158, v26, v27
	v_cvt_pk_bf16_f32 v159, v28, v29
	v_cvt_pk_bf16_f32 v160, v18, v19
	v_cvt_pk_bf16_f32 v161, v20, v21
	v_cvt_pk_bf16_f32 v162, v10, v11
	v_cvt_pk_bf16_f32 v163, v12, v13
	v_cvt_pk_bf16_f32 v164, v2, v3
	v_cvt_pk_bf16_f32 v165, v4, v5
	global_store_short v132, v150, s[6:7] offset:0
	global_store_short v132, v152, s[6:7] offset:32
	global_store_short v132, v154, s[6:7] offset:64
	global_store_short v132, v156, s[6:7] offset:96
	global_store_short v132, v158, s[6:7] offset:256
	global_store_short v132, v160, s[6:7] offset:288
	global_store_short v132, v162, s[6:7] offset:320
	global_store_short v132, v164, s[6:7] offset:352
	s_add_u32 s6, s6, s76
	s_addc_u32 s7, s7, 0
	global_store_short_d16_hi v132, v150, s[6:7] offset:0
	global_store_short_d16_hi v132, v152, s[6:7] offset:32
	global_store_short_d16_hi v132, v154, s[6:7] offset:64
	global_store_short_d16_hi v132, v156, s[6:7] offset:96
	global_store_short_d16_hi v132, v158, s[6:7] offset:256
	global_store_short_d16_hi v132, v160, s[6:7] offset:288
	global_store_short_d16_hi v132, v162, s[6:7] offset:320
	global_store_short_d16_hi v132, v164, s[6:7] offset:352
	s_add_u32 s6, s6, s76
	s_addc_u32 s7, s7, 0
	global_store_short v132, v151, s[6:7] offset:0
	global_store_short v132, v153, s[6:7] offset:32
	global_store_short v132, v155, s[6:7] offset:64
	global_store_short v132, v157, s[6:7] offset:96
	global_store_short v132, v159, s[6:7] offset:256
	global_store_short v132, v161, s[6:7] offset:288
	global_store_short v132, v163, s[6:7] offset:320
	global_store_short v132, v165, s[6:7] offset:352
	s_add_u32 s6, s6, s76
	s_addc_u32 s7, s7, 0
	global_store_short_d16_hi v132, v151, s[6:7] offset:0
	global_store_short_d16_hi v132, v153, s[6:7] offset:32
	global_store_short_d16_hi v132, v155, s[6:7] offset:64
	global_store_short_d16_hi v132, v157, s[6:7] offset:96
	global_store_short_d16_hi v132, v159, s[6:7] offset:256
	global_store_short_d16_hi v132, v161, s[6:7] offset:288
	global_store_short_d16_hi v132, v163, s[6:7] offset:320
	global_store_short_d16_hi v132, v165, s[6:7] offset:352
	v_readfirstlane_b32 s28, v190
	s_nop 3
	s_lshr_b32 s28, s28, 6
	s_lshr_b32 s29, s28, 2
	s_and_b32 s30, s28, 3
	v_and_b32_e32 v172, 15, v190
	v_bfe_u32 v173, v190, 4, 2
	v_and_b32_e32 v174, 7, v172
	v_xor_b32_e32 v175, v173, v174
	v_add_u32_e32 v176, 4, v173
	v_xor_b32_e32 v176, v176, v174
	v_lshlrev_b32_e32 v177, 10, v172
	s_lshl_b32 s31, s30, 7
	v_add_u32_e32 v177, s31, v177
	v_lshl_add_u32 v178, v175, 4, v177
	v_lshl_add_u32 v179, v176, 4, v177
	v_add_u32_e32 v180, 0x10000, v178
	v_add_u32_e32 v181, 0x10000, v179
	v_and_b32_e32 v182, 63, v190
	v_lshlrev_b32_e32 v182, 4, v182
	s_lshl_b32 s44, s30, 13
	s_lshl_b32 s45, s29, 16
	s_add_i32 s44, s44, s45
	s_add_i32 s44, s44, 0x8000
	v_mov_b32_e32 v183, s44
	s_lshl_b32 s45, s28, 3
	s_lshl_b32 s45, s45, s85
	v_add_u32_e32 v184, s45, v182
	s_lshl_b32 s46, 64, s85
	s_lshl_b32 s47, 1, s85
	s_cmp_eq_u32 s29, 0
	s_cbranch_scc0 .Lkvst_v_0
	ds_write_b128 v178, v[126:129] offset:32768
	ds_write_b128 v179, v[122:125] offset:32768
	ds_write_b128 v178, v[94:97] offset:33280
	ds_write_b128 v179, v[90:93] offset:33280
	ds_write_b128 v178, v[118:121] offset:49152
	ds_write_b128 v179, v[114:117] offset:49152
	ds_write_b128 v178, v[86:89] offset:49664
	ds_write_b128 v179, v[82:85] offset:49664
	ds_write_b128 v180, v[110:113] offset:32768
	ds_write_b128 v181, v[106:109] offset:32768
	ds_write_b128 v180, v[78:81] offset:33280
	ds_write_b128 v181, v[74:77] offset:33280
	ds_write_b128 v180, v[102:105] offset:49152
	ds_write_b128 v181, v[98:101] offset:49152
	ds_write_b128 v180, v[70:73] offset:49664
	ds_write_b128 v181, v[66:69] offset:49664

.Lkvst_v_3:
	s_waitcnt lgkmcnt(0)
	s_barrier
	v_xor_b32_e32 v132, 0, v182
	v_add_u32_e32 v132, v183, v132
	ds_read_b128 v[140:143], v132 offset:0
	v_xor_b32_e32 v133, 16, v182
	v_add_u32_e32 v133, v183, v133
	ds_read_b128 v[144:147], v133 offset:1024
	v_xor_b32_e32 v134, 32, v182
	v_add_u32_e32 v134, v183, v134
	ds_read_b128 v[148:151], v134 offset:2048
	v_xor_b32_e32 v135, 48, v182
	v_add_u32_e32 v135, v183, v135
	ds_read_b128 v[152:155], v135 offset:3072
	v_xor_b32_e32 v136, 64, v182
	v_add_u32_e32 v136, v183, v136
	ds_read_b128 v[156:159], v136 offset:4096
	v_xor_b32_e32 v137, 80, v182
	v_add_u32_e32 v137, v183, v137
	ds_read_b128 v[160:163], v137 offset:5120
	v_xor_b32_e32 v138, 96, v182
	v_add_u32_e32 v138, v183, v138
	ds_read_b128 v[164:167], v138 offset:6144
	v_xor_b32_e32 v139, 112, v182
	v_add_u32_e32 v139, v183, v139
	ds_read_b128 v[168:171], v139 offset:7168
	s_mov_b32 s24, s8
	s_mov_b32 s25, s9
	s_waitcnt lgkmcnt(7)
	global_store_dwordx4 v184, v[140:143], s[24:25]
	s_add_u32 s24, s24, s47
	s_addc_u32 s25, s25, 0
	s_waitcnt lgkmcnt(6)
	global_store_dwordx4 v184, v[144:147], s[24:25]
	s_add_u32 s24, s24, s47
	s_addc_u32 s25, s25, 0
	s_waitcnt lgkmcnt(5)
	global_store_dwordx4 v184, v[148:151], s[24:25]
	s_add_u32 s24, s24, s47
	s_addc_u32 s25, s25, 0
	s_waitcnt lgkmcnt(4)
	global_store_dwordx4 v184, v[152:155], s[24:25]
	s_add_u32 s24, s24, s47
	s_addc_u32 s25, s25, 0
	s_waitcnt lgkmcnt(3)
	global_store_dwordx4 v184, v[156:159], s[24:25]
	s_add_u32 s24, s24, s47
	s_addc_u32 s25, s25, 0
	s_waitcnt lgkmcnt(2)
	global_store_dwordx4 v184, v[160:163], s[24:25]
	s_add_u32 s24, s24, s47
	s_addc_u32 s25, s25, 0
	s_waitcnt lgkmcnt(1)
	global_store_dwordx4 v184, v[164:167], s[24:25]
	s_add_u32 s24, s24, s47
	s_addc_u32 s25, s25, 0
	s_waitcnt lgkmcnt(0)
	global_store_dwordx4 v184, v[168:171], s[24:25]
	s_barrier
	s_branch .LBB0_247
	global_store_dwordx4 v133, v[126:129], s[8:9] offset:0
	global_store_dwordx4 v133, v[122:125], s[8:9] offset:64
	global_store_dwordx4 v133, v[94:97], s[8:9] offset:512
	global_store_dwordx4 v133, v[90:93], s[8:9] offset:576
	s_add_u32 s8, s8, s70
	s_addc_u32 s9, s9, 0
	global_store_dwordx4 v133, v[118:121], s[8:9] offset:0
	global_store_dwordx4 v133, v[114:117], s[8:9] offset:64
	global_store_dwordx4 v133, v[86:89], s[8:9] offset:512
	global_store_dwordx4 v133, v[82:85], s[8:9] offset:576
	s_add_u32 s8, s8, s70
	s_addc_u32 s9, s9, 0
	global_store_dwordx4 v133, v[110:113], s[8:9] offset:0
	global_store_dwordx4 v133, v[106:109], s[8:9] offset:64
	global_store_dwordx4 v133, v[78:81], s[8:9] offset:512
	global_store_dwordx4 v133, v[74:77], s[8:9] offset:576
	s_add_u32 s8, s8, s70
	s_addc_u32 s9, s9, 0
	global_store_dwordx4 v133, v[102:105], s[8:9] offset:0
	global_store_dwordx4 v133, v[98:101], s[8:9] offset:64
	global_store_dwordx4 v133, v[70:73], s[8:9] offset:512
	global_store_dwordx4 v133, v[66:69], s[8:9] offset:576
	s_add_u32 s8, s8, s71
	s_addc_u32 s9, s9, 0
	global_store_dwordx4 v133, v[62:65], s[8:9] offset:0
	global_store_dwordx4 v133, v[58:61], s[8:9] offset:64
	global_store_dwordx4 v133, v[30:33], s[8:9] offset:512
	global_store_dwordx4 v133, v[26:29], s[8:9] offset:576
	s_add_u32 s8, s8, s70
	s_addc_u32 s9, s9, 0
	global_store_dwordx4 v133, v[54:57], s[8:9] offset:0
	global_store_dwordx4 v133, v[50:53], s[8:9] offset:64
	global_store_dwordx4 v133, v[22:25], s[8:9] offset:512
	global_store_dwordx4 v133, v[18:21], s[8:9] offset:576
	s_add_u32 s8, s8, s70
	s_addc_u32 s9, s9, 0
	global_store_dwordx4 v133, v[46:49], s[8:9] offset:0
	global_store_dwordx4 v133, v[42:45], s[8:9] offset:64
	global_store_dwordx4 v133, v[14:17], s[8:9] offset:512
	global_store_dwordx4 v133, v[10:13], s[8:9] offset:576
	s_add_u32 s8, s8, s70
	s_addc_u32 s9, s9, 0
	global_store_dwordx4 v133, v[38:41], s[8:9] offset:0
	global_store_dwordx4 v133, v[34:37], s[8:9] offset:64
	global_store_dwordx4 v133, v[6:9], s[8:9] offset:512
	global_store_dwordx4 v133, v[2:5], s[8:9] offset:576
	s_branch .LBB0_247
